# phase 5 loop software-pipelined: next token's 12 row loads issued at the top of the current token (v100-185 free), body unchanged
# baseline (speedup 1.0000x reference)
.LBB0_719:
	s_cmp_lt_i32 s74, 6
	s_cselect_b64 s[4:5], -1, 0
	s_and_b64 s[0:1], s[4:5], s[0:1]
	s_andn2_b64 vcc, exec, s[0:1]
	s_cbranch_vccnz .LBB0_727
	v_readlane_b32 s0, v254, 29
	s_cmpk_gt_i32 s0, 0x7fff
	s_movk_i32 s11, 0x7fff
	v_readlane_b32 s1, v254, 30
	s_cbranch_scc1 .LBB0_727
	v_lshlrev_b32_e32 v24, 5, v181
	v_mov_b32_e32 v25, 0
	s_waitcnt vmcnt(0)
	v_lshl_add_u64 v[20:21], s[44:45], 0, v[24:25]
	v_readlane_b32 s48, v254, 12
	v_add_co_u32_e32 v16, vcc, 0x1000, v20
	s_mov_b64 s[0:1], 0x1000
	v_readlane_b32 s58, v254, 22
	v_readlane_b32 s59, v254, 23
	v_readlane_b32 s60, v254, 24
	v_readlane_b32 s61, v254, 25
	v_addc_co_u32_e32 v17, vcc, 0, v21, vcc
	v_lshl_add_u64 v[20:21], v[20:21], 0, s[0:1]
	s_nop 0
	global_load_dwordx4 v[0:3], v24, s[58:59]
	s_nop 0
	global_load_dwordx4 v[4:7], v24, s[60:61]
	global_load_dwordx4 v[8:11], v24, s[60:61] offset:16
	global_load_dwordx4 v[12:15], v24, s[58:59] offset:16
	v_readlane_b32 s62, v254, 26
	global_load_dwordx4 v[16:19], v[16:17], off
	v_readlane_b32 s63, v254, 27
	global_load_dwordx4 v[20:23], v[20:21], off offset:16
	v_readlane_b32 s62, v254, 29
	v_readlane_b32 s63, v254, 30
	v_readlane_b32 s50, v254, 14
	v_readlane_b32 s51, v254, 15
	s_ashr_i32 s63, s62, 31
	v_lshrrev_b32_e32 v26, 1, v181
	v_readlane_b32 s54, v254, 18
	v_readlane_b32 s55, v254, 19
	v_readlane_b32 s56, v254, 20
	v_readlane_b32 s57, v254, 21
	v_and_b32_e32 v26, 28, v26
	v_mov_b32_e32 v27, v25
	s_lshl_b64 s[50:51], s[62:63], 5
	v_readlane_b32 s52, v254, 16
	v_readlane_b32 s53, v254, 17
	v_mov_b32_e32 v28, 0x1200
	s_mov_b64 s[2:3], 0x2880000
	v_lshlrev_b32_e32 v24, 4, v181
	s_lshl_b64 s[54:55], s[62:63], 10
	s_lshl_b64 s[56:57], s[62:63], 9
	s_lshl_b64 s[58:59], s[62:63], 12
	v_lshl_add_u64 v[56:57], s[62:63], 4, v[26:27]
	v_or_b32_e32 v26, s50, v26
	v_mov_b32_e32 v27, s51
	v_readlane_b32 s49, v254, 13
	s_ashr_i32 s35, s34, 31
	s_mov_b64 s[44:45], 0x1ad00000
	s_mov_b64 s[46:47], 0x7d00800
	s_lshl_b64 s[52:53], s[62:63], 11
	v_lshl_add_u64 v[54:55], s[42:43], 0, v[24:25]
	v_mad_i64_i32 v[58:59], s[60:61], s62, v28, v[24:25]
	v_or_b32_e32 v62, s54, v24
	v_lshl_add_u64 v[28:29], s[56:57], 0, v[24:25]
	v_or_b32_e32 v24, s58, v24
	v_mov_b32_e32 v25, s59
	v_lshl_add_u64 v[64:65], v[26:27], 0, s[2:3]
	s_mov_b32 s2, s62
	v_cmp_gt_u32_e64 s[0:1], 32, v181
	s_mul_hi_i32 s9, s34, 0x1200
	s_mul_i32 s8, s34, 0x1200
	s_mov_b64 s[16:17], 0x3d00000
	s_mov_b32 s14, 0x3d00000
	s_mov_b32 s15, 0xffff0000
	v_mov_b32_e32 v75, 0x3a27c5ac
	s_mov_b32 s48, 0x800000
	s_mov_b32 s49, 0xc2fc0000
	s_lshl_b64 s[18:19], s[34:35], 4
	s_lshl_b64 s[20:21], s[34:35], 5
	s_lshl_b64 s[22:23], s[34:35], 11
	s_lshl_b64 s[28:29], s[34:35], 10
	s_lshl_b64 s[30:31], s[34:35], 9
	s_lshl_b64 s[38:39], s[34:35], 12
	v_lshl_or_b32 v60, v181, 5, s52
	v_mov_b32_e32 v61, s53
	v_mov_b32_e32 v63, s55
	v_lshl_add_u64 v[66:67], v[28:29], 0, s[44:45]
	v_lshl_add_u64 v[68:69], v[24:25], 0, s[46:47]
	v_mov_b32_e32 v76, 0x42800000
	v_not_b32_e32 v77, 63
	v_writelane_b32 v254, s2, 29
	s_mov_b64 s[44:45], s[62:63]
	s_waitcnt vmcnt(5)
	v_mov_b32_e32 v70, v1
	v_mov_b32_e32 v71, v3
	s_waitcnt vmcnt(4)
	v_mov_b32_e32 v72, v5
	v_mov_b32_e32 v73, v7
	v_mov_b32_e32 v1, v2
	v_mov_b32_e32 v5, v6
	s_waitcnt vmcnt(2)
	v_mov_b32_e32 v2, v13
	v_mov_b32_e32 v3, v15
	v_mov_b32_e32 v6, v9
	v_mov_b32_e32 v7, v11
	v_mov_b32_e32 v13, v14
	v_mov_b32_e32 v9, v10
	s_waitcnt vmcnt(1)
	v_mov_b32_e32 v10, v17
	v_mov_b32_e32 v11, v19
	v_mov_b32_e32 v17, v18
	s_waitcnt vmcnt(0)
	v_mov_b32_e32 v14, v21
	v_mov_b32_e32 v15, v23
	v_mov_b32_e32 v21, v22
	v_writelane_b32 v254, s3, 30
	v_mov_b64_e32 v[100:101], v[60:61]
	v_mov_b64_e32 v[102:103], v[68:69]
	v_mov_b64_e32 v[104:105], v[62:63]
	v_mov_b64_e32 v[106:107], v[64:65]
	v_mov_b64_e32 v[108:109], v[58:59]
	v_mov_b64_e32 v[110:111], v[56:57]
	s_mov_b32 s98, s44
	s_mov_b32 s99, s45
	s_and_b32 s100, s98, 0xfff
	s_cmp_lg_u32 s100, 0
	s_cselect_b64 s[100:101], -1, 0
	v_cndmask_b32_e64 v118, 0, 1, s[100:101]
	v_mov_b32_e32 v119, s99
	v_sub_co_u32_e32 v118, vcc, s98, v118
	v_lshl_add_u64 v[122:123], s[72:73], 0, v[100:101]
	s_nop 0
	v_subbrev_co_u32_e32 v119, vcc, 0, v119, vcc
	v_lshl_add_u64 v[124:125], v[122:123], 0, s[16:17]
	v_add_co_u32_e32 v122, vcc, s14, v122
	v_lshlrev_b64 v[118:119], 12, v[118:119]
	s_nop 0
	v_addc_co_u32_e32 v123, vcc, 0, v123, vcc
	global_load_dwordx4 v[146:149], v[122:123], off
	global_load_dwordx4 v[134:137], v[124:125], off offset:16
	v_lshl_add_u64 v[122:123], s[72:73], 0, v[102:103]
	v_lshl_add_u64 v[118:119], v[54:55], 0, v[118:119]
	global_load_dwordx4 v[138:141], v[122:123], off
	global_load_dwordx4 v[150:153], v[118:119], off offset:2048
	v_lshl_add_u64 v[118:119], s[72:73], 0, v[104:105]
	v_add_co_u32_e32 v122, vcc, 0x1cd00000, v118
	v_lshl_add_u64 v[124:125], s[72:73], 0, v[106:107]
	s_nop 0
	v_addc_co_u32_e32 v123, vcc, 0, v119, vcc
	global_load_dwordx4 v[142:145], v[122:123], off
	global_load_dword v174, v[124:125], off
	v_mov_b32_e32 v126, 0
	v_mov_b32_e32 v178, 0
	v_mov_b32_e32 v179, 0
	v_mov_b32_e32 v180, 0
	v_mov_b32_e32 v127, 0
	v_mov_b32_e32 v128, 0
	v_mov_b32_e32 v129, 0
	v_mov_b32_e32 v122, 0
	v_mov_b32_e32 v123, 0
	v_mov_b32_e32 v124, 0
	v_mov_b32_e32 v125, 0
	v_mov_b32_e32 v130, 0
	v_mov_b32_e32 v131, 0
	v_mov_b32_e32 v132, 0
	v_mov_b32_e32 v133, 0
	s_and_saveexec_b64 s[46:47], s[0:1]
	s_cbranch_execz .Lmy_p5_a
	v_lshl_add_u64 v[122:123], s[72:73], 0, v[108:109]
	v_add_co_u32_e32 v126, vcc, 0xfd00000, v122
	v_lshl_add_u64 v[128:129], s[72:73], 0, v[110:111]
	s_nop 0
	v_addc_co_u32_e32 v127, vcc, 0, v123, vcc
	v_add_co_u32_e32 v178, vcc, 0x2b80000, v128
	global_load_dwordx4 v[130:133], v[126:127], off
	global_load_dwordx4 v[122:125], v[126:127], off offset:512
	v_addc_co_u32_e32 v179, vcc, 0, v129, vcc
	v_add_co_u32_e32 v182, vcc, 0x2c00000, v128
	s_nop 1
	v_addc_co_u32_e32 v183, vcc, 0, v129, vcc
	v_add_co_u32_e32 v184, vcc, 0x2c80000, v128
	s_nop 1
	v_addc_co_u32_e32 v185, vcc, 0, v129, vcc
	global_load_dwordx4 v[126:129], v[126:127], off offset:1024
	s_nop 0
	global_load_dword v180, v[178:179], off
	s_nop 0
	global_load_dword v179, v[182:183], off
	global_load_dword v178, v[184:185], off
.Lmy_p5_a:
	s_or_b64 exec, exec, s[46:47]
	s_waitcnt vmcnt(0)
	s_branch .LBB0_723

.LBB0_723:
	s_and_b32 s2, s44, 0xfff
	s_cmp_lg_u32 s2, 0
	s_cselect_b64 s[2:3], -1, 0
	v_cndmask_b32_e64 v18, 0, 1, s[2:3]
	v_mov_b32_e32 v19, s45
	v_sub_co_u32_e32 v18, vcc, s44, v18
	v_lshl_add_u64 v[22:23], s[72:73], 0, v[60:61]
	s_nop 0
	v_subbrev_co_u32_e32 v19, vcc, 0, v19, vcc
	v_lshl_add_u64 v[24:25], v[22:23], 0, s[16:17]
	v_add_co_u32_e32 v22, vcc, s14, v22
	v_lshlrev_b64 v[18:19], 12, v[18:19]
	s_nop 0
	v_addc_co_u32_e32 v23, vcc, 0, v23, vcc
	v_lshl_add_u64 v[22:23], s[72:73], 0, v[68:69]
	v_lshl_add_u64 v[18:19], v[54:55], 0, v[18:19]
	v_lshl_add_u64 v[18:19], s[72:73], 0, v[62:63]
	v_add_co_u32_e32 v22, vcc, 0x1cd00000, v18
	v_lshl_add_u64 v[24:25], s[72:73], 0, v[64:65]
	s_nop 0
	v_addc_co_u32_e32 v23, vcc, 0, v19, vcc
	v_mov_b32_e32 v26, 0
	v_mov_b32_e32 v78, 0
	v_mov_b32_e32 v79, 0
	v_mov_b32_e32 v80, 0
	v_mov_b32_e32 v27, 0
	v_mov_b32_e32 v28, 0
	v_mov_b32_e32 v29, 0
	v_mov_b32_e32 v22, 0
	v_mov_b32_e32 v23, 0
	v_mov_b32_e32 v24, 0
	v_mov_b32_e32 v25, 0
	v_mov_b32_e32 v30, 0
	v_mov_b32_e32 v31, 0
	v_mov_b32_e32 v32, 0
	v_mov_b32_e32 v33, 0
	s_and_saveexec_b64 s[46:47], s[0:1]
	s_cbranch_execz .LBB0_725
	v_lshl_add_u64 v[22:23], s[72:73], 0, v[58:59]
	v_add_co_u32_e32 v26, vcc, 0xfd00000, v22
	v_lshl_add_u64 v[28:29], s[72:73], 0, v[56:57]
	s_nop 0
	v_addc_co_u32_e32 v27, vcc, 0, v23, vcc
	v_add_co_u32_e32 v78, vcc, 0x2b80000, v28
	v_addc_co_u32_e32 v79, vcc, 0, v29, vcc
	v_add_co_u32_e32 v82, vcc, 0x2c00000, v28
	s_nop 1
	v_addc_co_u32_e32 v83, vcc, 0, v29, vcc
	v_add_co_u32_e32 v84, vcc, 0x2c80000, v28
	s_nop 1
	v_addc_co_u32_e32 v85, vcc, 0, v29, vcc
	s_nop 0
	s_nop 0
.LBB0_725:
	s_or_b64 exec, exec, s[46:47]
	s_waitcnt vmcnt(1)
	v_mov_b64_e32 v[46:47], v[146:147]
	v_mov_b64_e32 v[48:49], v[148:149]
	v_mov_b64_e32 v[34:35], v[134:135]
	v_mov_b64_e32 v[36:37], v[136:137]
	v_mov_b64_e32 v[38:39], v[138:139]
	v_mov_b64_e32 v[40:41], v[140:141]
	v_mov_b64_e32 v[50:51], v[150:151]
	v_mov_b64_e32 v[52:53], v[152:153]
	v_mov_b64_e32 v[42:43], v[142:143]
	v_mov_b64_e32 v[44:45], v[144:145]
	v_mov_b64_e32 v[30:31], v[130:131]
	v_mov_b64_e32 v[32:33], v[132:133]
	v_mov_b64_e32 v[22:23], v[122:123]
	v_mov_b64_e32 v[24:25], v[124:125]
	v_mov_b64_e32 v[26:27], v[126:127]
	v_mov_b64_e32 v[28:29], v[128:129]
	v_mov_b64_e32 v[78:79], v[178:179]
	v_mov_b32_e32 v74, v174
	v_mov_b32_e32 v80, v180
	v_lshl_add_u64 v[100:101], v[60:61], 0, s[22:23]
	v_lshl_add_u64 v[102:103], v[68:69], 0, s[38:39]
	v_lshl_add_u64 v[104:105], v[62:63], 0, s[28:29]
	v_lshl_add_u64 v[106:107], v[64:65], 0, s[20:21]
	v_lshl_add_u64 v[108:109], v[58:59], 0, s[8:9]
	v_lshl_add_u64 v[110:111], v[56:57], 0, s[18:19]
	s_add_u32 s98, s44, s34
	s_addc_u32 s99, s45, s35
	s_cmp_lt_i32 s98, 0x8000
	s_cbranch_scc0 .Lmy_p5_skip
	s_and_b32 s100, s98, 0xfff
	s_cmp_lg_u32 s100, 0
	s_cselect_b64 s[100:101], -1, 0
	v_cndmask_b32_e64 v118, 0, 1, s[100:101]
	v_mov_b32_e32 v119, s99
	v_sub_co_u32_e32 v118, vcc, s98, v118
	v_lshl_add_u64 v[122:123], s[72:73], 0, v[100:101]
	s_nop 0
	v_subbrev_co_u32_e32 v119, vcc, 0, v119, vcc
	v_lshl_add_u64 v[124:125], v[122:123], 0, s[16:17]
	v_add_co_u32_e32 v122, vcc, s14, v122
	v_lshlrev_b64 v[118:119], 12, v[118:119]
	s_nop 0
	v_addc_co_u32_e32 v123, vcc, 0, v123, vcc
	global_load_dwordx4 v[146:149], v[122:123], off
	global_load_dwordx4 v[134:137], v[124:125], off offset:16
	v_lshl_add_u64 v[122:123], s[72:73], 0, v[102:103]
	v_lshl_add_u64 v[118:119], v[54:55], 0, v[118:119]
	global_load_dwordx4 v[138:141], v[122:123], off
	global_load_dwordx4 v[150:153], v[118:119], off offset:2048
	v_lshl_add_u64 v[118:119], s[72:73], 0, v[104:105]
	v_add_co_u32_e32 v122, vcc, 0x1cd00000, v118
	v_lshl_add_u64 v[124:125], s[72:73], 0, v[106:107]
	s_nop 0
	v_addc_co_u32_e32 v123, vcc, 0, v119, vcc
	global_load_dwordx4 v[142:145], v[122:123], off
	global_load_dword v174, v[124:125], off
	v_mov_b32_e32 v126, 0
	v_mov_b32_e32 v178, 0
	v_mov_b32_e32 v179, 0
	v_mov_b32_e32 v180, 0
	v_mov_b32_e32 v127, 0
	v_mov_b32_e32 v128, 0
	v_mov_b32_e32 v129, 0
	v_mov_b32_e32 v122, 0
	v_mov_b32_e32 v123, 0
	v_mov_b32_e32 v124, 0
	v_mov_b32_e32 v125, 0
	v_mov_b32_e32 v130, 0
	v_mov_b32_e32 v131, 0
	v_mov_b32_e32 v132, 0
	v_mov_b32_e32 v133, 0
	s_and_saveexec_b64 s[46:47], s[0:1]
	s_cbranch_execz .Lmy_p5_b
	v_lshl_add_u64 v[122:123], s[72:73], 0, v[108:109]
	v_add_co_u32_e32 v126, vcc, 0xfd00000, v122
	v_lshl_add_u64 v[128:129], s[72:73], 0, v[110:111]
	s_nop 0
	v_addc_co_u32_e32 v127, vcc, 0, v123, vcc
	v_add_co_u32_e32 v178, vcc, 0x2b80000, v128
	global_load_dwordx4 v[130:133], v[126:127], off
	global_load_dwordx4 v[122:125], v[126:127], off offset:512
	v_addc_co_u32_e32 v179, vcc, 0, v129, vcc
	v_add_co_u32_e32 v182, vcc, 0x2c00000, v128
	s_nop 1
	v_addc_co_u32_e32 v183, vcc, 0, v129, vcc
	v_add_co_u32_e32 v184, vcc, 0x2c80000, v128
	s_nop 1
	v_addc_co_u32_e32 v185, vcc, 0, v129, vcc
	global_load_dwordx4 v[126:129], v[126:127], off offset:1024
	s_nop 0
	global_load_dword v180, v[178:179], off
	s_nop 0
	global_load_dword v179, v[182:183], off
	global_load_dword v178, v[184:185], off

.Lmy_p5_skip:
	v_mov_b32_e32 v84, v46
	v_mov_b32_e32 v85, v34
	v_mov_b32_e32 v86, v47
	v_mov_b32_e32 v87, v35
	v_pk_add_f32 v[84:85], v[84:85], v[86:87]
	v_mov_b32_e32 v86, v48
	v_mov_b32_e32 v87, v36
	v_mov_b32_e32 v88, v49
	v_mov_b32_e32 v89, v37
	v_pk_add_f32 v[86:87], v[86:87], v[88:89]
	v_mov_b32_e32 v94, v46
	v_pk_add_f32 v[84:85], v[84:85], v[86:87]
	v_mov_b32_e32 v95, v48
	v_add_f32_e32 v81, v84, v85
	v_mov_b32_e32 v48, v47
	v_mov_b32_e32 v98, v34
	v_add_f32_dpp v81, v81, v81 quad_perm:[1,0,3,2] row_mask:0xf bank_mask:0xf bound_ctrl:1
	v_mov_b32_e32 v99, v36
	v_mov_b32_e32 v36, v35
	v_add_f32_dpp v81, v81, v81 quad_perm:[2,3,0,1] row_mask:0xf bank_mask:0xf bound_ctrl:1
	v_cndmask_b32_e64 v82, 0, 1.0, s[2:3]
	v_lshlrev_b32_e32 v87, 16, v51
	v_add_f32_dpp v81, v81, v81 row_half_mirror row_mask:0xf bank_mask:0xf bound_ctrl:1
	v_mul_f32_e32 v84, 0x3c800000, v81
	v_pk_add_f32 v[94:95], v[94:95], v[84:85] op_sel_hi:[1,0] neg_lo:[0,1] neg_hi:[0,1]
	v_pk_add_f32 v[46:47], v[48:49], v[84:85] op_sel_hi:[1,0] neg_lo:[0,1] neg_hi:[0,1]
	v_mov_b32_e32 v48, v94
	v_mov_b32_e32 v49, v46
	v_pk_mul_f32 v[48:49], v[48:49], v[48:49]
	v_mov_b32_e32 v96, v95
	v_mov_b32_e32 v97, v47
	v_pk_mul_f32 v[96:97], v[96:97], v[96:97]
	v_pk_add_f32 v[98:99], v[98:99], v[84:85] op_sel_hi:[1,0] neg_lo:[0,1] neg_hi:[0,1]
	v_pk_add_f32 v[34:35], v[36:37], v[84:85] op_sel_hi:[1,0] neg_lo:[0,1] neg_hi:[0,1]
	v_add_f32_e32 v48, v48, v49
	v_mov_b32_e32 v36, v98
	v_mov_b32_e32 v37, v34
	v_add_f32_e32 v48, v48, v96
	v_pk_mul_f32 v[36:37], v[36:37], v[36:37]
	v_add_f32_e32 v48, v48, v97
	v_mov_b32_e32 v84, v99
	v_mov_b32_e32 v85, v35
	v_add_f32_e32 v36, v48, v36
	v_pk_mul_f32 v[84:85], v[84:85], v[84:85]
	v_add_f32_e32 v36, v36, v37
	v_add_f32_e32 v36, v36, v84
	v_add_f32_e32 v36, v36, v85
	v_lshlrev_b32_e32 v86, 16, v50
	v_and_b32_e32 v51, 0xffff0000, v51
	v_add_f32_dpp v36, v36, v36 quad_perm:[1,0,3,2] row_mask:0xf bank_mask:0xf bound_ctrl:1
	v_and_b32_e32 v50, 0xffff0000, v50
	v_lshlrev_b32_e32 v91, 16, v39
	v_add_f32_dpp v36, v36, v36 quad_perm:[2,3,0,1] row_mask:0xf bank_mask:0xf bound_ctrl:1
	v_lshlrev_b32_e32 v90, 16, v38
	v_and_b32_e32 v39, 0xffff0000, v39
	v_add_f32_dpp v36, v36, v36 row_half_mirror row_mask:0xf bank_mask:0xf bound_ctrl:1
	v_fmamk_f32 v36, v36, 0x3c800000, v75
	v_mul_f32_e32 v37, 0x4b800000, v36
	v_cmp_gt_f32_e32 vcc, s48, v36
	v_and_b32_e32 v38, 0xffff0000, v38
	v_pk_fma_f32 v[50:51], v[82:83], v[50:51], v[38:39] op_sel_hi:[0,1,1] neg_lo:[0,0,1] neg_hi:[0,0,1]
	v_cndmask_b32_e32 v36, v36, v37, vcc
	v_rsq_f32_e32 v81, v36
	v_lshlrev_b32_e32 v89, 16, v53
	v_lshlrev_b32_e32 v88, 16, v52
	v_and_b32_e32 v53, 0xffff0000, v53
	v_and_b32_e32 v52, 0xffff0000, v52
	v_pk_fma_f32 v[38:39], v[50:51], v[10:11], v[38:39]
	v_lshlrev_b32_e32 v51, 16, v41
	v_lshlrev_b32_e32 v50, 16, v40
	v_and_b32_e32 v41, 0xffff0000, v41
	v_and_b32_e32 v40, 0xffff0000, v40
	v_pk_fma_f32 v[48:49], v[82:83], v[52:53], v[40:41] op_sel_hi:[0,1,1] neg_lo:[0,0,1] neg_hi:[0,0,1]
	v_pk_fma_f32 v[40:41], v[48:49], v[14:15], v[40:41]
	v_mul_f32_e32 v48, 0x45800000, v81
	v_cndmask_b32_e32 v48, v81, v48, vcc
	v_pk_mul_f32 v[46:47], v[48:49], v[46:47] op_sel_hi:[0,1]
	v_pk_fma_f32 v[46:47], v[46:47], v[70:71], v[72:73]
	v_lshlrev_b32_e32 v93, 16, v43
	v_lshlrev_b32_e32 v92, 16, v42
	v_and_b32_e32 v43, 0xffff0000, v43
	v_and_b32_e32 v42, 0xffff0000, v42
	v_pk_fma_f32 v[88:89], v[82:83], v[88:89], v[50:51] op_sel_hi:[0,1,1] neg_lo:[0,0,1] neg_hi:[0,0,1]
	v_pk_fma_f32 v[38:39], v[74:75], v[38:39], v[46:47] op_sel_hi:[0,1,1]
	v_pk_mul_f32 v[34:35], v[48:49], v[34:35] op_sel_hi:[0,1]
	v_pk_fma_f32 v[86:87], v[82:83], v[86:87], v[90:91] op_sel_hi:[0,1,1] neg_lo:[0,0,1] neg_hi:[0,0,1]
	v_pk_fma_f32 v[36:37], v[88:89], v[20:21], v[50:51]
	v_pk_mul_f32 v[50:51], v[48:49], v[94:95] op_sel_hi:[0,1]
	v_pk_mul_f32 v[38:39], v[38:39], v[42:43]
	v_pk_mul_f32 v[42:43], v[48:49], v[98:99] op_sel_hi:[0,1]
	v_pk_fma_f32 v[34:35], v[34:35], v[2:3], v[6:7]
	v_pk_fma_f32 v[86:87], v[86:87], v[16:17], v[90:91]
	v_lshlrev_b32_e32 v91, 16, v45
	v_lshlrev_b32_e32 v90, 16, v44
	v_and_b32_e32 v45, 0xffff0000, v45
	v_and_b32_e32 v44, 0xffff0000, v44
	v_pk_fma_f32 v[50:51], v[50:51], v[0:1], v[4:5]
	v_pk_fma_f32 v[42:43], v[42:43], v[12:13], v[8:9]
	v_pk_fma_f32 v[34:35], v[74:75], v[40:41], v[34:35] op_sel_hi:[0,1,1]
	v_pk_fma_f32 v[50:51], v[74:75], v[86:87], v[50:51] op_sel_hi:[0,1,1]
	v_pk_fma_f32 v[36:37], v[74:75], v[36:37], v[42:43] op_sel_hi:[0,1,1]
	v_pk_mul_f32 v[34:35], v[34:35], v[44:45]
	v_pk_mul_f32 v[50:51], v[50:51], v[92:93]
	v_pk_mul_f32 v[36:37], v[36:37], v[90:91]
	v_bfe_u32 v40, v35, 16, 1
	v_bfe_u32 v41, v34, 16, 1
	v_bfe_u32 v42, v39, 16, 1
	v_bfe_u32 v43, v38, 16, 1
	v_add3_u32 v38, v38, v43, s11
	v_add3_u32 v39, v39, v42, s11
	v_add3_u32 v34, v34, v41, s11
	v_add3_u32 v35, v35, v40, s11
	v_bfe_u32 v40, v50, 16, 1
	v_bfe_u32 v41, v51, 16, 1
	v_bfe_u32 v42, v36, 16, 1
	v_bfe_u32 v43, v37, 16, 1
	v_add3_u32 v37, v37, v43, s11
	v_add3_u32 v36, v36, v42, s11
	v_add3_u32 v41, v51, v41, s11
	v_add3_u32 v40, v50, v40, s11
	v_lshrrev_b32_e32 v40, 16, v40
	v_lshrrev_b32_e32 v41, 16, v41
	v_lshrrev_b32_e32 v36, 16, v36
	v_lshrrev_b32_e32 v37, 16, v37
	v_add_co_u32_e32 v18, vcc, 0x18d00000, v18
	v_and_or_b32 v37, v35, s15, v37
	v_and_or_b32 v36, v34, s15, v36
	v_and_or_b32 v35, v39, s15, v41
	v_and_or_b32 v34, v38, s15, v40
	v_addc_co_u32_e32 v19, vcc, 0, v19, vcc
	global_store_dwordx4 v[18:19], v[34:37], off
	s_and_saveexec_b64 s[46:47], s[0:1]
	s_cbranch_execz .LBB0_722
	v_max3_f32 v18, v80, v79, v78
	v_sub_f32_e32 v19, v80, v18
	v_cmp_gt_f32_e32 vcc, s49, v19
	v_lshlrev_b32_e32 v43, 16, v23
	v_lshlrev_b32_e32 v42, 16, v30
	v_cndmask_b32_e32 v34, 0, v76, vcc
	v_add_f32_e32 v19, v19, v34
	v_exp_f32_e32 v19, v19
	v_sub_f32_e32 v34, v79, v18
	v_cndmask_b32_e32 v35, 0, v77, vcc
	v_cmp_gt_f32_e32 vcc, s49, v34
	v_sub_f32_e32 v18, v78, v18
	v_ldexp_f32 v19, v19, v35
	v_cndmask_b32_e32 v35, 0, v76, vcc
	v_cmp_gt_f32_e64 s[2:3], s49, v18
	v_add_f32_e32 v34, v34, v35
	v_exp_f32_e32 v34, v34
	v_cndmask_b32_e64 v35, 0, v76, s[2:3]
	v_add_f32_e32 v18, v18, v35
	v_exp_f32_e32 v35, v18
	v_cndmask_b32_e32 v18, 0, v77, vcc
	v_ldexp_f32 v18, v34, v18
	v_cndmask_b32_e64 v34, 0, v77, s[2:3]
	v_ldexp_f32 v34, v35, v34
	v_add_f32_e32 v35, v19, v18
	v_add_f32_e32 v35, v34, v35
	v_div_scale_f32 v36, s[2:3], v35, v35, 1.0
	v_rcp_f32_e32 v37, v36
	v_and_b32_e32 v23, 0xffff0000, v23
	v_and_b32_e32 v41, 0xffff0000, v31
	v_pk_mul_f32 v[42:43], v[18:19], v[42:43] op_sel:[1,0] op_sel_hi:[0,1]
	v_fma_f32 v38, -v36, v37, 1.0
	v_fmac_f32_e32 v37, v38, v37
	v_div_scale_f32 v38, vcc, 1.0, v35, 1.0
	v_mul_f32_e32 v39, v38, v37
	v_fma_f32 v40, -v36, v39, v38
	v_fmac_f32_e32 v39, v40, v37
	v_fma_f32 v36, -v36, v39, v38
	v_lshlrev_b32_e32 v38, 16, v22
	v_and_b32_e32 v40, 0xffff0000, v22
	v_and_b32_e32 v22, 0xffff0000, v30
	v_div_fmas_f32 v36, v36, v37, v39
	v_lshlrev_b32_e32 v39, 16, v31
	v_pk_mul_f32 v[22:23], v[18:19], v[22:23] op_sel:[1,0] op_sel_hi:[0,1]
	v_lshlrev_b32_e32 v31, 16, v27
	v_lshlrev_b32_e32 v30, 16, v26
	v_and_b32_e32 v27, 0xffff0000, v27
	v_and_b32_e32 v26, 0xffff0000, v26
	v_pk_fma_f32 v[38:39], v[18:19], v[38:39], v[42:43]
	v_pk_fma_f32 v[22:23], v[18:19], v[40:41], v[22:23]
	v_pk_fma_f32 v[30:31], v[34:35], v[30:31], v[38:39] op_sel_hi:[0,1,1]
	v_pk_fma_f32 v[22:23], v[34:35], v[26:27], v[22:23] op_sel_hi:[0,1,1]
	v_lshlrev_b32_e32 v26, 16, v24
	v_and_b32_e32 v38, 0xffff0000, v24
	v_lshlrev_b32_e32 v41, 16, v25
	v_lshlrev_b32_e32 v40, 16, v32
	v_and_b32_e32 v25, 0xffff0000, v25
	v_and_b32_e32 v24, 0xffff0000, v32
	v_lshlrev_b32_e32 v27, 16, v33
	v_and_b32_e32 v39, 0xffff0000, v33
	v_pk_mul_f32 v[40:41], v[18:19], v[40:41] op_sel:[1,0] op_sel_hi:[0,1]
	v_pk_mul_f32 v[24:25], v[18:19], v[24:25] op_sel:[1,0] op_sel_hi:[0,1]
	v_lshlrev_b32_e32 v33, 16, v29
	v_lshlrev_b32_e32 v32, 16, v28
	v_and_b32_e32 v29, 0xffff0000, v29
	v_and_b32_e32 v28, 0xffff0000, v28
	v_pk_fma_f32 v[26:27], v[18:19], v[26:27], v[40:41]
	v_pk_fma_f32 v[18:19], v[18:19], v[38:39], v[24:25]
	v_div_fixup_f32 v36, v36, v35, 1.0
	v_pk_fma_f32 v[18:19], v[34:35], v[28:29], v[18:19] op_sel_hi:[0,1,1]
	v_pk_mul_f32 v[22:23], v[36:37], v[22:23] op_sel_hi:[0,1]
	v_pk_fma_f32 v[26:27], v[34:35], v[32:33], v[26:27] op_sel_hi:[0,1,1]
	v_pk_mul_f32 v[18:19], v[36:37], v[18:19] op_sel_hi:[0,1]
	v_pk_mul_f32 v[30:31], v[36:37], v[30:31] op_sel_hi:[0,1]
	v_pk_mul_f32 v[26:27], v[36:37], v[26:27] op_sel_hi:[0,1]
	v_bfe_u32 v24, v19, 16, 1
	v_bfe_u32 v25, v18, 16, 1
	v_bfe_u32 v28, v23, 16, 1
	v_bfe_u32 v29, v22, 16, 1
	v_add3_u32 v22, v22, v29, s11
	v_add3_u32 v23, v23, v28, s11
	v_add3_u32 v18, v18, v25, s11
	v_add3_u32 v19, v19, v24, s11
	v_bfe_u32 v24, v30, 16, 1
	v_bfe_u32 v25, v31, 16, 1
	v_bfe_u32 v28, v26, 16, 1
	v_bfe_u32 v29, v27, 16, 1
	v_add3_u32 v27, v27, v29, s11
	v_add3_u32 v26, v26, v28, s11
	v_add3_u32 v25, v31, v25, s11
	v_add3_u32 v24, v30, v24, s11
	v_lshrrev_b32_e32 v28, 16, v24
	v_lshrrev_b32_e32 v29, 16, v25
	v_lshrrev_b32_e32 v24, 16, v26
	v_lshrrev_b32_e32 v25, 16, v27
	v_and_or_b32 v25, v19, s15, v25
	v_and_or_b32 v24, v18, s15, v24
	v_and_or_b32 v23, v23, s15, v29
	v_and_or_b32 v22, v22, s15, v28
	v_lshl_add_u64 v[18:19], s[72:73], 0, v[66:67]
	global_store_dwordx4 v[18:19], v[22:25], off
	s_branch .LBB0_722
